# GEMM loop 1 (in-projection): LDS-DMA staging rebalanced 4/4 per super-phase (As[b][0] staged one super-phase later, SP2 waits vmcnt(6)); plus earlier p3a and EpiResid edits
# baseline (speedup 1.0000x reference)
.LBB0_257:
	s_or_b64 exec, exec, s[42:43]
	s_lshl_b32 s2, s80, 7
	v_lshl_add_u64 v[156:157], v[90:91], 0, s[2:3]
	s_mov_b64 s[42:43], 0x100
	v_lshl_add_u64 v[94:95], v[156:157], 0, s[42:43]
	v_add_u32_e32 v167, s74, v162
	v_cndmask_b32_e64 v225, v151, v95, s[6:7]
	v_cndmask_b32_e64 v224, v150, v94, s[6:7]
	ds_read_b128 v[94:97], v167
	ds_read_b128 v[152:155], v167 offset:1024
	ds_read_b128 v[168:171], v167 offset:2048
	ds_read_b128 v[172:175], v167 offset:3072
	v_add_u32_e32 v167, s75, v162
	ds_read_b128 v[176:179], v167
	ds_read_b128 v[180:183], v167 offset:1024
	ds_read_b128 v[184:187], v167 offset:2048
	ds_read_b128 v[188:191], v167 offset:3072
	s_add_u32 s2, s8, s2
	s_addc_u32 s42, s9, 0
	s_add_u32 s2, s2, 0x100
	s_addc_u32 s42, s42, 0
	s_and_b64 s[6:7], s[6:7], exec
	s_cselect_b32 s7, s42, s29
	s_cselect_b32 s6, s2, s31
	s_mov_b64 s[42:43], 0x80
	v_lshl_add_u64 v[156:157], v[156:157], 0, s[42:43]
	v_lshl_add_u64 v[226:227], v[156:157], 0, v[138:139]
	s_mov_b32 m0, s67
	ds_read_b128 v[192:195], v164
	ds_read_b128 v[196:199], v164 offset:1024
	ds_read_b128 v[200:203], v164 offset:2048
	ds_read_b128 v[204:207], v164 offset:3072
	ds_read_b128 v[208:211], v164 offset:4096
	ds_read_b128 v[212:215], v164 offset:5120
	ds_read_b128 v[216:219], v164 offset:6144
	ds_read_b128 v[220:223], v164 offset:7168
	global_load_lds_dwordx4 v[226:227], off
	v_lshl_add_u64 v[226:227], v[156:157], 0, v[142:143]
	s_mov_b32 m0, s68
	s_mov_b64 s[42:43], 0x80000
	global_load_lds_dwordx4 v[226:227], off
	v_lshl_add_u64 v[156:157], v[156:157], 0, s[42:43]
	v_lshl_add_u64 v[226:227], v[156:157], 0, v[138:139]
	s_add_i32 m0, s15, 0xc000
	s_nop 0
	global_load_lds_dwordx4 v[226:227], off
	v_lshl_add_u64 v[156:157], v[156:157], 0, v[142:143]
	s_add_i32 m0, s15, 0xe000
	s_nop 0
	global_load_lds_dwordx4 v[156:157], off
	s_waitcnt vmcnt(8)
	s_waitcnt lgkmcnt(0)
	s_barrier
	s_setprio 1
	s_waitcnt lgkmcnt(0)
	v_mfma_f32_16x16x32_bf16 v[70:73], v[94:97], v[192:195], v[70:73]
	v_mfma_f32_16x16x32_bf16 v[66:69], v[168:171], v[192:195], v[66:69]
	v_mfma_f32_16x16x32_bf16 v[62:65], v[94:97], v[200:203], v[62:65]
	v_mfma_f32_16x16x32_bf16 v[58:61], v[168:171], v[200:203], v[58:61]
	v_mfma_f32_16x16x32_bf16 v[54:57], v[94:97], v[208:211], v[54:57]
	v_mfma_f32_16x16x32_bf16 v[50:53], v[168:171], v[208:211], v[50:53]
	v_mfma_f32_16x16x32_bf16 v[46:49], v[94:97], v[216:219], v[46:49]
	v_mfma_f32_16x16x32_bf16 v[42:45], v[168:171], v[216:219], v[42:45]
	v_mfma_f32_16x16x32_bf16 v[70:73], v[152:155], v[196:199], v[70:73]
	v_mfma_f32_16x16x32_bf16 v[66:69], v[172:175], v[196:199], v[66:69]
	v_mfma_f32_16x16x32_bf16 v[62:65], v[152:155], v[204:207], v[62:65]
	v_mfma_f32_16x16x32_bf16 v[58:61], v[172:175], v[204:207], v[58:61]
	v_mfma_f32_16x16x32_bf16 v[54:57], v[152:155], v[212:215], v[54:57]
	v_mfma_f32_16x16x32_bf16 v[50:53], v[172:175], v[212:215], v[50:53]
	v_mfma_f32_16x16x32_bf16 v[46:49], v[152:155], v[220:223], v[46:49]
	v_mfma_f32_16x16x32_bf16 v[42:45], v[172:175], v[220:223], v[42:45]
	s_setprio 0
	s_setprio 1
	v_mfma_f32_16x16x32_bf16 v[134:137], v[176:179], v[192:195], v[134:137]
	v_mfma_f32_16x16x32_bf16 v[130:133], v[184:187], v[192:195], v[130:133]
	v_mfma_f32_16x16x32_bf16 v[126:129], v[176:179], v[200:203], v[126:129]
	v_mfma_f32_16x16x32_bf16 v[122:125], v[184:187], v[200:203], v[122:125]
	v_mfma_f32_16x16x32_bf16 v[118:121], v[176:179], v[208:211], v[118:121]
	v_mfma_f32_16x16x32_bf16 v[114:117], v[184:187], v[208:211], v[114:117]
	v_mfma_f32_16x16x32_bf16 v[110:113], v[176:179], v[216:219], v[110:113]
	v_mfma_f32_16x16x32_bf16 v[106:109], v[184:187], v[216:219], v[106:109]
	v_mfma_f32_16x16x32_bf16 v[134:137], v[180:183], v[196:199], v[134:137]
	v_mfma_f32_16x16x32_bf16 v[130:133], v[188:191], v[196:199], v[130:133]
	v_mfma_f32_16x16x32_bf16 v[126:129], v[180:183], v[204:207], v[126:129]
	v_mfma_f32_16x16x32_bf16 v[122:125], v[188:191], v[204:207], v[122:125]
	v_mfma_f32_16x16x32_bf16 v[118:121], v[180:183], v[212:215], v[118:121]
	v_mfma_f32_16x16x32_bf16 v[114:117], v[188:191], v[212:215], v[114:117]
	v_mfma_f32_16x16x32_bf16 v[110:113], v[180:183], v[220:223], v[110:113]
	v_mfma_f32_16x16x32_bf16 v[106:109], v[188:191], v[220:223], v[106:109]
	s_setprio 0
	s_barrier
	s_add_i32 s2, s74, s48
	v_lshl_add_u64 v[156:157], s[6:7], 0, v[140:141]
	s_mov_b32 m0, s2
	ds_read_b128 v[192:195], v164 offset:16384
	ds_read_b128 v[196:199], v164 offset:17408
	ds_read_b128 v[200:203], v164 offset:18432
	ds_read_b128 v[204:207], v164 offset:19456
	ds_read_b128 v[208:211], v164 offset:20480
	ds_read_b128 v[212:215], v164 offset:21504
	ds_read_b128 v[216:219], v164 offset:22528
	ds_read_b128 v[220:223], v164 offset:23552
	global_load_lds_dwordx4 v[156:157], off
	s_add_i32 m0, s2, 0x2000
	s_add_u32 s42, s6, 0x80000
	v_lshl_add_u64 v[226:227], s[6:7], 0, v[144:145]
	s_addc_u32 s43, s7, 0
	s_add_i32 s2, s75, s48
	global_load_lds_dwordx4 v[226:227], off
	v_lshl_add_u64 v[228:229], s[42:43], 0, v[140:141]
	s_mov_b32 m0, s2
	s_nop 0
	global_load_lds_dwordx4 v[228:229], off
	v_lshl_add_u64 v[228:229], s[42:43], 0, v[144:145]
	s_add_i32 m0, s2, 0x2000
	s_nop 0
	global_load_lds_dwordx4 v[228:229], off
	s_waitcnt vmcnt(6)
	s_waitcnt lgkmcnt(0)
	s_barrier
	s_setprio 1
	s_waitcnt lgkmcnt(0)
	v_mfma_f32_16x16x32_bf16 v[34:37], v[94:97], v[192:195], v[34:37]
	v_mfma_f32_16x16x32_bf16 v[26:29], v[168:171], v[192:195], v[26:29]
	v_mfma_f32_16x16x32_bf16 v[22:25], v[94:97], v[200:203], v[22:25]
	v_mfma_f32_16x16x32_bf16 v[18:21], v[168:171], v[200:203], v[18:21]
	v_mfma_f32_16x16x32_bf16 v[14:17], v[94:97], v[208:211], v[14:17]
	v_mfma_f32_16x16x32_bf16 v[10:13], v[168:171], v[208:211], v[10:13]
	v_mfma_f32_16x16x32_bf16 v[6:9], v[94:97], v[216:219], v[6:9]
	v_mfma_f32_16x16x32_bf16 v[2:5], v[168:171], v[216:219], v[2:5]
	v_mfma_f32_16x16x32_bf16 v[34:37], v[152:155], v[196:199], v[34:37]
	v_mfma_f32_16x16x32_bf16 v[26:29], v[172:175], v[196:199], v[26:29]
	v_mfma_f32_16x16x32_bf16 v[22:25], v[152:155], v[204:207], v[22:25]
	v_mfma_f32_16x16x32_bf16 v[18:21], v[172:175], v[204:207], v[18:21]
	v_mfma_f32_16x16x32_bf16 v[14:17], v[152:155], v[212:215], v[14:17]
	v_mfma_f32_16x16x32_bf16 v[10:13], v[172:175], v[212:215], v[10:13]
	v_mfma_f32_16x16x32_bf16 v[6:9], v[152:155], v[220:223], v[6:9]
	v_mfma_f32_16x16x32_bf16 v[2:5], v[172:175], v[220:223], v[2:5]
	s_setprio 0
	s_setprio 1
	v_mfma_f32_16x16x32_bf16 v[98:101], v[184:187], v[192:195], v[98:101]
	v_mfma_f32_16x16x32_bf16 v[86:89], v[176:179], v[200:203], v[86:89]
	v_mfma_f32_16x16x32_bf16 v[82:85], v[184:187], v[200:203], v[82:85]
	v_mfma_f32_16x16x32_bf16 v[78:81], v[176:179], v[208:211], v[78:81]
	v_mfma_f32_16x16x32_bf16 v[74:77], v[184:187], v[208:211], v[74:77]
	v_mfma_f32_16x16x32_bf16 v[38:41], v[176:179], v[216:219], v[38:41]
	v_mfma_f32_16x16x32_bf16 v[30:33], v[184:187], v[216:219], v[30:33]
	v_mfma_f32_16x16x32_bf16 v[94:97], v[176:179], v[192:195], v[102:105]
	v_mfma_f32_16x16x32_bf16 v[98:101], v[188:191], v[196:199], v[98:101]
	v_mfma_f32_16x16x32_bf16 v[86:89], v[180:183], v[204:207], v[86:89]
	v_mfma_f32_16x16x32_bf16 v[82:85], v[188:191], v[204:207], v[82:85]
	v_mfma_f32_16x16x32_bf16 v[78:81], v[180:183], v[212:215], v[78:81]
	v_mfma_f32_16x16x32_bf16 v[74:77], v[188:191], v[212:215], v[74:77]
	v_mfma_f32_16x16x32_bf16 v[38:41], v[180:183], v[220:223], v[38:41]
	v_mfma_f32_16x16x32_bf16 v[30:33], v[188:191], v[220:223], v[30:33]
	v_mfma_f32_16x16x32_bf16 v[94:97], v[180:183], v[196:199], v[94:97]
	s_setprio 0
	s_barrier
	s_add_i32 s2, 0, 0x18000
	v_add_u32_e32 v167, s2, v162
	s_add_i32 s44, 0, 0x1c000
	ds_read_b128 v[102:105], v167
	ds_read_b128 v[152:155], v167 offset:1024
	ds_read_b128 v[168:171], v167 offset:2048
	ds_read_b128 v[172:175], v167 offset:3072
	v_add_u32_e32 v167, s44, v162
	ds_read_b128 v[176:179], v167
	ds_read_b128 v[180:183], v167 offset:1024
	ds_read_b128 v[184:187], v167 offset:2048
	ds_read_b128 v[188:191], v167 offset:3072
	s_mov_b64 s[42:43], 0x80000
	v_lshl_add_u64 v[232:233], v[224:225], 0, v[138:139]
	s_mov_b32 m0, s15
	ds_read_b128 v[192:195], v164 offset:32768
	ds_read_b128 v[196:199], v164 offset:33792
	ds_read_b128 v[200:203], v164 offset:34816
	ds_read_b128 v[204:207], v164 offset:35840
	ds_read_b128 v[208:211], v164 offset:36864
	ds_read_b128 v[212:215], v164 offset:37888
	ds_read_b128 v[216:219], v164 offset:38912
	ds_read_b128 v[220:223], v164 offset:39936
	global_load_lds_dwordx4 v[232:233], off
	v_lshl_add_u64 v[232:233], v[224:225], 0, v[142:143]
	s_mov_b32 m0, s17
	v_lshl_add_u64 v[224:225], v[224:225], 0, s[42:43]
	global_load_lds_dwordx4 v[232:233], off
	v_lshl_add_u64 v[232:233], v[224:225], 0, v[138:139]
	s_mov_b32 m0, s49
	s_nop 0
	global_load_lds_dwordx4 v[232:233], off
	v_lshl_add_u64 v[224:225], v[224:225], 0, v[142:143]
	s_mov_b32 m0, s50
	s_nop 0
	global_load_lds_dwordx4 v[224:225], off
	s_waitcnt vmcnt(8)
	s_waitcnt lgkmcnt(0)
	s_barrier
	s_setprio 1
	s_waitcnt lgkmcnt(0)
	v_mfma_f32_16x16x32_bf16 v[70:73], v[102:105], v[192:195], v[70:73]
	v_mfma_f32_16x16x32_bf16 v[66:69], v[168:171], v[192:195], v[66:69]
	v_mfma_f32_16x16x32_bf16 v[62:65], v[102:105], v[200:203], v[62:65]
	v_mfma_f32_16x16x32_bf16 v[58:61], v[168:171], v[200:203], v[58:61]
	v_mfma_f32_16x16x32_bf16 v[54:57], v[102:105], v[208:211], v[54:57]
	v_mfma_f32_16x16x32_bf16 v[50:53], v[168:171], v[208:211], v[50:53]
	v_mfma_f32_16x16x32_bf16 v[46:49], v[102:105], v[216:219], v[46:49]
	v_mfma_f32_16x16x32_bf16 v[42:45], v[168:171], v[216:219], v[42:45]
	v_mfma_f32_16x16x32_bf16 v[70:73], v[152:155], v[196:199], v[70:73]
	v_mfma_f32_16x16x32_bf16 v[66:69], v[172:175], v[196:199], v[66:69]
	v_mfma_f32_16x16x32_bf16 v[62:65], v[152:155], v[204:207], v[62:65]
	v_mfma_f32_16x16x32_bf16 v[58:61], v[172:175], v[204:207], v[58:61]
	v_mfma_f32_16x16x32_bf16 v[54:57], v[152:155], v[212:215], v[54:57]
	v_mfma_f32_16x16x32_bf16 v[50:53], v[172:175], v[212:215], v[50:53]
	v_mfma_f32_16x16x32_bf16 v[46:49], v[152:155], v[220:223], v[46:49]
	v_mfma_f32_16x16x32_bf16 v[42:45], v[172:175], v[220:223], v[42:45]
	s_setprio 0
	s_setprio 1
	v_mfma_f32_16x16x32_bf16 v[134:137], v[176:179], v[192:195], v[134:137]
	v_mfma_f32_16x16x32_bf16 v[130:133], v[184:187], v[192:195], v[130:133]
	v_mfma_f32_16x16x32_bf16 v[126:129], v[176:179], v[200:203], v[126:129]
	v_mfma_f32_16x16x32_bf16 v[122:125], v[184:187], v[200:203], v[122:125]
	v_mfma_f32_16x16x32_bf16 v[118:121], v[176:179], v[208:211], v[118:121]
	v_mfma_f32_16x16x32_bf16 v[114:117], v[184:187], v[208:211], v[114:117]
	v_mfma_f32_16x16x32_bf16 v[110:113], v[176:179], v[216:219], v[110:113]
	v_mfma_f32_16x16x32_bf16 v[106:109], v[184:187], v[216:219], v[106:109]
	v_mfma_f32_16x16x32_bf16 v[134:137], v[180:183], v[196:199], v[134:137]
	v_mfma_f32_16x16x32_bf16 v[130:133], v[188:191], v[196:199], v[130:133]
	v_mfma_f32_16x16x32_bf16 v[126:129], v[180:183], v[204:207], v[126:129]
	v_mfma_f32_16x16x32_bf16 v[122:125], v[188:191], v[204:207], v[122:125]
	v_mfma_f32_16x16x32_bf16 v[118:121], v[180:183], v[212:215], v[118:121]
	v_mfma_f32_16x16x32_bf16 v[114:117], v[188:191], v[212:215], v[114:117]
	v_mfma_f32_16x16x32_bf16 v[110:113], v[180:183], v[220:223], v[110:113]
	v_mfma_f32_16x16x32_bf16 v[106:109], v[188:191], v[220:223], v[106:109]
	s_setprio 0
	s_barrier
	s_add_i32 s2, s2, s48
	v_lshl_add_u64 v[156:157], v[156:157], 0, s[20:21]
	s_mov_b32 m0, s2
	ds_read_b128 v[192:195], v164 offset:49152
	ds_read_b128 v[196:199], v164 offset:50176
	ds_read_b128 v[200:203], v164 offset:51200
	ds_read_b128 v[204:207], v164 offset:52224
	ds_read_b128 v[208:211], v164 offset:53248
	ds_read_b128 v[212:215], v164 offset:54272
	ds_read_b128 v[216:219], v164 offset:55296
	ds_read_b128 v[220:223], v164 offset:56320
	global_load_lds_dwordx4 v[156:157], off
	s_add_i32 m0, s2, 0x2000
	s_add_u32 s6, s6, 0x80080
	v_lshl_add_u64 v[156:157], v[226:227], 0, s[20:21]
	s_addc_u32 s7, s7, 0
	s_add_i32 s2, s44, s48
	global_load_lds_dwordx4 v[156:157], off
	v_lshl_add_u64 v[156:157], s[6:7], 0, v[140:141]
	s_mov_b32 m0, s2
	s_nop 0
	global_load_lds_dwordx4 v[156:157], off
	v_lshl_add_u64 v[156:157], s[6:7], 0, v[144:145]
	s_add_i32 m0, s2, 0x2000
	s_nop 0
	global_load_lds_dwordx4 v[156:157], off
	s_waitcnt vmcnt(6)
	s_waitcnt lgkmcnt(0)
	s_barrier
	s_setprio 1
	s_waitcnt lgkmcnt(0)
	v_mfma_f32_16x16x32_bf16 v[34:37], v[102:105], v[192:195], v[34:37]
	v_mfma_f32_16x16x32_bf16 v[26:29], v[168:171], v[192:195], v[26:29]
	v_mfma_f32_16x16x32_bf16 v[22:25], v[102:105], v[200:203], v[22:25]
	v_mfma_f32_16x16x32_bf16 v[18:21], v[168:171], v[200:203], v[18:21]
	v_mfma_f32_16x16x32_bf16 v[14:17], v[102:105], v[208:211], v[14:17]
	v_mfma_f32_16x16x32_bf16 v[10:13], v[168:171], v[208:211], v[10:13]
	v_mfma_f32_16x16x32_bf16 v[6:9], v[102:105], v[216:219], v[6:9]
	v_mfma_f32_16x16x32_bf16 v[2:5], v[168:171], v[216:219], v[2:5]
	v_mfma_f32_16x16x32_bf16 v[34:37], v[152:155], v[196:199], v[34:37]
	v_mfma_f32_16x16x32_bf16 v[26:29], v[172:175], v[196:199], v[26:29]
	v_mfma_f32_16x16x32_bf16 v[22:25], v[152:155], v[204:207], v[22:25]
	v_mfma_f32_16x16x32_bf16 v[18:21], v[172:175], v[204:207], v[18:21]
	v_mfma_f32_16x16x32_bf16 v[14:17], v[152:155], v[212:215], v[14:17]
	v_mfma_f32_16x16x32_bf16 v[10:13], v[172:175], v[212:215], v[10:13]
	v_mfma_f32_16x16x32_bf16 v[6:9], v[152:155], v[220:223], v[6:9]
	v_mfma_f32_16x16x32_bf16 v[2:5], v[172:175], v[220:223], v[2:5]
	s_setprio 0
	s_setprio 1
	v_mfma_f32_16x16x32_bf16 v[94:97], v[176:179], v[192:195], v[94:97]
	v_mfma_f32_16x16x32_bf16 v[102:105], v[180:183], v[196:199], v[94:97]
	v_mfma_f32_16x16x32_bf16 v[94:97], v[184:187], v[192:195], v[98:101]
	v_mfma_f32_16x16x32_bf16 v[86:89], v[176:179], v[200:203], v[86:89]
	v_mfma_f32_16x16x32_bf16 v[82:85], v[184:187], v[200:203], v[82:85]
	v_mfma_f32_16x16x32_bf16 v[78:81], v[176:179], v[208:211], v[78:81]
	v_mfma_f32_16x16x32_bf16 v[74:77], v[184:187], v[208:211], v[74:77]
	v_mfma_f32_16x16x32_bf16 v[38:41], v[176:179], v[216:219], v[38:41]
	v_mfma_f32_16x16x32_bf16 v[30:33], v[184:187], v[216:219], v[30:33]
	v_mfma_f32_16x16x32_bf16 v[98:101], v[188:191], v[196:199], v[94:97]
	v_mfma_f32_16x16x32_bf16 v[86:89], v[180:183], v[204:207], v[86:89]
	v_mfma_f32_16x16x32_bf16 v[82:85], v[188:191], v[204:207], v[82:85]
	v_mfma_f32_16x16x32_bf16 v[78:81], v[180:183], v[212:215], v[78:81]
	v_mfma_f32_16x16x32_bf16 v[74:77], v[188:191], v[212:215], v[74:77]
	v_mfma_f32_16x16x32_bf16 v[38:41], v[180:183], v[220:223], v[38:41]
	v_mfma_f32_16x16x32_bf16 v[30:33], v[188:191], v[220:223], v[30:33]
	s_setprio 0
	s_barrier
	s_add_i32 s2, s80, 2
	s_cmp_gt_u32 s80, 29
	s_cbranch_scc1 .LBB0_259
	s_mov_b32 s80, s2
	s_branch .LBB0_237
